# FF1 epilogues (P7/P15): non-temporal hint on the 16 H stores
# speedup vs baseline: 1.0116x; 1.0116x over previous
; __device__ __forceinline__ unsigned pk2(float lo, float hi) { f32x2 v = {lo, hi}; bf16x2_t b = __builtin_convertvector(v, bf16x2_t); return __builtin_bit_cast(unsigned, b); }
; __device__ __forceinline__ float silu_f(float a) { return a * __builtin_amdgcn_rcpf(1.0f + __expf(-a)); }
;     __device__ __forceinline__ void operator()(const f32x4 (&acc)[2][2][4][2], const Unit& u, int wr, int wc, int fr, int fq) const {
;         const int row0 = u.pm * BM + wr * 64 + fr; const int col0 = u.pn * HALF + wc * 32 + 8 * fq;
; #pragma unroll
;         for (int ai = 0; ai < 2; ++ai)
; #pragma unroll
;             for (int m = 0; m < 4; ++m) { const int row = row0 + ai * HALF + m * 16;
;                 const f32x4 a0 = acc[ai][0][m][0], a1 = acc[ai][0][m][1], b0 = acc[ai][1][m][0], b1 = acc[ai][1][m][1];
;                 u32x4 w; w.x = pk2(silu_f(a0[0]) * b0[0], silu_f(a0[1]) * b0[1]); w.y = pk2(silu_f(a0[2]) * b0[2], silu_f(a0[3]) * b0[3]);
;                 w.z = pk2(silu_f(a1[0]) * b1[0], silu_f(a1[1]) * b1[1]); w.w = pk2(silu_f(a1[2]) * b1[2], silu_f(a1[3]) * b1[3]);
;                 *(u32x4*)(H + (size_t)row * ldh + col0) = w; }
.LBB0_717:
	s_mov_b32 s77, 1
	v_mul_f32_e32 v151, 0xbfb8aa3b, v124
	v_exp_f32_e32 v151, v151
	v_mul_f32_e32 v153, 0xbfb8aa3b, v125
	v_exp_f32_e32 v153, v153
	v_mul_f32_e32 v157, 0xbfb8aa3b, v127
	v_add_f32_e32 v151, 1.0, v151
	v_rcp_f32_e32 v156, v151
	v_add_f32_e32 v151, 1.0, v153
	v_mul_f32_e32 v153, 0xbfb8aa3b, v126
	v_exp_f32_e32 v153, v153
	v_exp_f32_e32 v159, v157
	v_rcp_f32_e32 v157, v151
	v_lshl_or_b32 v154, s71, 7, v146
	v_add_f32_e32 v151, 1.0, v153
	v_rcp_f32_e32 v158, v151
	v_add_f32_e32 v151, 1.0, v159
	v_rcp_f32_e32 v159, v151
	v_pk_mul_f32 v[124:125], v[124:125], v[156:157]
	v_lshl_add_u32 v150, s38, 8, v144
	v_pk_mul_f32 v[120:121], v[124:125], v[120:121]
	v_pk_mul_f32 v[124:125], v[126:127], v[158:159]
	v_cvt_pk_bf16_f32 v120, v120, v121
	v_mul_f32_e32 v121, 0xbfb8aa3b, v116
	v_pk_mul_f32 v[122:123], v[124:125], v[122:123]
	v_exp_f32_e32 v124, v121
	v_mul_f32_e32 v121, 0xbfb8aa3b, v117
	v_exp_f32_e32 v125, v121
	v_cvt_pk_bf16_f32 v121, v122, v123
	v_add_f32_e32 v122, 1.0, v124
	v_mul_f32_e32 v124, 0xbfb8aa3b, v118
	v_add_f32_e32 v123, 1.0, v125
	v_mul_f32_e32 v125, 0xbfb8aa3b, v119
	v_exp_f32_e32 v124, v124
	v_exp_f32_e32 v125, v125
	v_rcp_f32_e32 v122, v122
	v_rcp_f32_e32 v123, v123
	v_add_f32_e32 v124, 1.0, v124
	v_add_f32_e32 v125, 1.0, v125
	v_rcp_f32_e32 v124, v124
	v_rcp_f32_e32 v125, v125
	v_pk_mul_f32 v[116:117], v[116:117], v[122:123]
	v_ashrrev_i32_e32 v155, 31, v154
	v_pk_mul_f32 v[112:113], v[116:117], v[112:113]
	s_andn2_b64 vcc, exec, s[0:1]
	v_cvt_pk_bf16_f32 v122, v112, v113
	v_pk_mul_f32 v[112:113], v[118:119], v[124:125]
	v_mul_f32_e32 v118, 0xbfb8aa3b, v110
	v_pk_mul_f32 v[112:113], v[112:113], v[114:115]
	v_lshlrev_b64 v[114:115], 1, v[154:155]
	v_cvt_pk_bf16_f32 v123, v112, v113
	v_mov_b64_e32 v[112:113], s[8:9]
	v_mad_i64_i32 v[116:117], s[40:41], v150, s70, v[112:113]
	v_lshl_add_u64 v[116:117], v[116:117], 0, v[114:115]
	global_store_dwordx4 v[116:117], v[120:123], off nt
	v_mul_f32_e32 v116, 0xbfb8aa3b, v108
	v_mul_f32_e32 v117, 0xbfb8aa3b, v109
	v_exp_f32_e32 v116, v116
	v_exp_f32_e32 v117, v117
	v_mul_f32_e32 v119, 0xbfb8aa3b, v111
	v_exp_f32_e32 v118, v118
	v_exp_f32_e32 v119, v119
	v_add_f32_e32 v116, 1.0, v116
	v_add_f32_e32 v117, 1.0, v117
	v_rcp_f32_e32 v116, v116
	v_rcp_f32_e32 v117, v117
	v_add_f32_e32 v118, 1.0, v118
	v_add_f32_e32 v119, 1.0, v119
	v_rcp_f32_e32 v118, v118
	v_rcp_f32_e32 v119, v119
	v_pk_mul_f32 v[108:109], v[108:109], v[116:117]
	v_or_b32_e32 v120, 16, v150
	v_pk_mul_f32 v[104:105], v[108:109], v[104:105]
	v_pk_mul_f32 v[108:109], v[110:111], v[118:119]
	v_cvt_pk_bf16_f32 v104, v104, v105
	v_mul_f32_e32 v105, 0xbfb8aa3b, v100
	v_pk_mul_f32 v[106:107], v[108:109], v[106:107]
	v_exp_f32_e32 v108, v105
	v_mul_f32_e32 v105, 0xbfb8aa3b, v101
	v_exp_f32_e32 v109, v105
	v_cvt_pk_bf16_f32 v105, v106, v107
	v_add_f32_e32 v106, 1.0, v108
	v_mul_f32_e32 v108, 0xbfb8aa3b, v102
	v_add_f32_e32 v107, 1.0, v109
	v_mul_f32_e32 v109, 0xbfb8aa3b, v103
	v_exp_f32_e32 v108, v108
	v_exp_f32_e32 v109, v109
	v_rcp_f32_e32 v106, v106
	v_rcp_f32_e32 v107, v107
	v_add_f32_e32 v108, 1.0, v108
	v_add_f32_e32 v109, 1.0, v109
	v_rcp_f32_e32 v108, v108
	v_rcp_f32_e32 v109, v109
	v_pk_mul_f32 v[100:101], v[100:101], v[106:107]
	s_mov_b64 s[0:1], -1
	v_pk_mul_f32 v[96:97], v[100:101], v[96:97]
	v_or_b32_e32 v100, 32, v150
	v_cvt_pk_bf16_f32 v106, v96, v97
	v_pk_mul_f32 v[96:97], v[102:103], v[108:109]
	s_nop 0
	v_pk_mul_f32 v[96:97], v[96:97], v[98:99]
	v_mul_f32_e32 v98, 0xbfb8aa3b, v94
	v_cvt_pk_bf16_f32 v107, v96, v97
	v_mad_i64_i32 v[96:97], s[40:41], v120, s70, v[112:113]
	v_lshl_add_u64 v[96:97], v[96:97], 0, v[114:115]
	global_store_dwordx4 v[96:97], v[104:107], off nt
	v_mul_f32_e32 v96, 0xbfb8aa3b, v92
	v_mul_f32_e32 v97, 0xbfb8aa3b, v93
	v_exp_f32_e32 v96, v96
	v_exp_f32_e32 v97, v97
	v_mul_f32_e32 v99, 0xbfb8aa3b, v95
	v_exp_f32_e32 v98, v98
	v_exp_f32_e32 v99, v99
	v_add_f32_e32 v96, 1.0, v96
	v_add_f32_e32 v97, 1.0, v97
	v_rcp_f32_e32 v96, v96
	v_rcp_f32_e32 v97, v97
	v_add_f32_e32 v98, 1.0, v98
	v_add_f32_e32 v99, 1.0, v99
	v_rcp_f32_e32 v98, v98
	v_rcp_f32_e32 v99, v99
	v_pk_mul_f32 v[92:93], v[92:93], v[96:97]
	s_nop 0
	v_pk_mul_f32 v[88:89], v[92:93], v[88:89]
	v_pk_mul_f32 v[92:93], v[94:95], v[98:99]
	v_cvt_pk_bf16_f32 v88, v88, v89
	v_mul_f32_e32 v89, 0xbfb8aa3b, v84
	v_pk_mul_f32 v[90:91], v[92:93], v[90:91]
	v_exp_f32_e32 v92, v89
	v_mul_f32_e32 v89, 0xbfb8aa3b, v85
	v_exp_f32_e32 v93, v89
	v_cvt_pk_bf16_f32 v89, v90, v91
	v_add_f32_e32 v90, 1.0, v92
	v_mul_f32_e32 v92, 0xbfb8aa3b, v86
	v_add_f32_e32 v91, 1.0, v93
	v_mul_f32_e32 v93, 0xbfb8aa3b, v87
	v_exp_f32_e32 v92, v92
	v_exp_f32_e32 v93, v93
	v_rcp_f32_e32 v90, v90
	v_rcp_f32_e32 v91, v91
	v_add_f32_e32 v92, 1.0, v92
	v_add_f32_e32 v93, 1.0, v93
	v_rcp_f32_e32 v92, v92
	v_rcp_f32_e32 v93, v93
	v_pk_mul_f32 v[84:85], v[84:85], v[90:91]
	s_nop 0
	v_pk_mul_f32 v[80:81], v[84:85], v[80:81]
	v_or_b32_e32 v84, 48, v150
	v_cvt_pk_bf16_f32 v90, v80, v81
	v_pk_mul_f32 v[80:81], v[86:87], v[92:93]
	s_nop 0
	v_pk_mul_f32 v[80:81], v[80:81], v[82:83]
	v_mul_f32_e32 v82, 0xbfb8aa3b, v78
	v_cvt_pk_bf16_f32 v91, v80, v81
	v_mad_i64_i32 v[80:81], s[40:41], v100, s70, v[112:113]
	v_lshl_add_u64 v[80:81], v[80:81], 0, v[114:115]
	global_store_dwordx4 v[80:81], v[88:91], off nt
	v_mul_f32_e32 v80, 0xbfb8aa3b, v76
	v_mul_f32_e32 v81, 0xbfb8aa3b, v77
	v_exp_f32_e32 v80, v80
	v_exp_f32_e32 v81, v81
	v_mul_f32_e32 v83, 0xbfb8aa3b, v79
	v_exp_f32_e32 v82, v82
	v_exp_f32_e32 v83, v83
	v_add_f32_e32 v80, 1.0, v80
	v_add_f32_e32 v81, 1.0, v81
	v_rcp_f32_e32 v80, v80
	v_rcp_f32_e32 v81, v81
	v_add_f32_e32 v82, 1.0, v82
	v_add_f32_e32 v83, 1.0, v83
; __device__ __forceinline__ unsigned pk2(float lo, float hi) { f32x2 v = {lo, hi}; bf16x2_t b = __builtin_convertvector(v, bf16x2_t); return __builtin_bit_cast(unsigned, b); }
; __device__ __forceinline__ float silu_f(float a) { return a * __builtin_amdgcn_rcpf(1.0f + __expf(-a)); }
;     __device__ __forceinline__ void operator()(const f32x4 (&acc)[2][2][4][2], const Unit& u, int wr, int wc, int fr, int fq) const {
;     ...
;             for (int m = 0; m < 4; ++m) { const int row = row0 + ai * HALF + m * 16;
;                 const f32x4 a0 = acc[ai][0][m][0], a1 = acc[ai][0][m][1], b0 = acc[ai][1][m][0], b1 = acc[ai][1][m][1];
;                 u32x4 w; w.x = pk2(silu_f(a0[0]) * b0[0], silu_f(a0[1]) * b0[1]); w.y = pk2(silu_f(a0[2]) * b0[2], silu_f(a0[3]) * b0[3]);
;                 w.z = pk2(silu_f(a1[0]) * b1[0], silu_f(a1[1]) * b1[1]); w.w = pk2(silu_f(a1[2]) * b1[2], silu_f(a1[3]) * b1[3]);
;                 *(u32x4*)(H + (size_t)row * ldh + col0) = w; }
	v_rcp_f32_e32 v82, v82
	v_rcp_f32_e32 v83, v83
	v_pk_mul_f32 v[76:77], v[76:77], v[80:81]
	s_nop 0
	v_pk_mul_f32 v[72:73], v[76:77], v[72:73]
	v_pk_mul_f32 v[76:77], v[78:79], v[82:83]
	v_cvt_pk_bf16_f32 v72, v72, v73
	v_mul_f32_e32 v73, 0xbfb8aa3b, v68
	v_pk_mul_f32 v[74:75], v[76:77], v[74:75]
	v_exp_f32_e32 v76, v73
	v_mul_f32_e32 v73, 0xbfb8aa3b, v69
	v_exp_f32_e32 v77, v73
	v_cvt_pk_bf16_f32 v73, v74, v75
	v_add_f32_e32 v74, 1.0, v76
	v_mul_f32_e32 v76, 0xbfb8aa3b, v70
	v_add_f32_e32 v75, 1.0, v77
	v_mul_f32_e32 v77, 0xbfb8aa3b, v71
	v_exp_f32_e32 v76, v76
	v_exp_f32_e32 v77, v77
	v_rcp_f32_e32 v74, v74
	v_rcp_f32_e32 v75, v75
	v_add_f32_e32 v76, 1.0, v76
	v_add_f32_e32 v77, 1.0, v77
	v_rcp_f32_e32 v76, v76
	v_rcp_f32_e32 v77, v77
	v_pk_mul_f32 v[68:69], v[68:69], v[74:75]
	s_nop 0
	v_pk_mul_f32 v[64:65], v[68:69], v[64:65]
	v_add_u32_e32 v68, 0x80, v150
	v_cvt_pk_bf16_f32 v74, v64, v65
	v_pk_mul_f32 v[64:65], v[70:71], v[76:77]
	s_nop 0
	v_pk_mul_f32 v[64:65], v[64:65], v[66:67]
	v_mul_f32_e32 v66, 0xbfb8aa3b, v62
	v_cvt_pk_bf16_f32 v75, v64, v65
	v_mad_i64_i32 v[64:65], s[40:41], v84, s70, v[112:113]
	v_lshl_add_u64 v[64:65], v[64:65], 0, v[114:115]
	global_store_dwordx4 v[64:65], v[72:75], off nt
	v_mul_f32_e32 v64, 0xbfb8aa3b, v60
	v_mul_f32_e32 v65, 0xbfb8aa3b, v61
	v_exp_f32_e32 v64, v64
	v_exp_f32_e32 v65, v65
	v_mul_f32_e32 v67, 0xbfb8aa3b, v63
	v_exp_f32_e32 v66, v66
	v_exp_f32_e32 v67, v67
	v_add_f32_e32 v64, 1.0, v64
	v_add_f32_e32 v65, 1.0, v65
	v_rcp_f32_e32 v64, v64
	v_rcp_f32_e32 v65, v65
	v_add_f32_e32 v66, 1.0, v66
	v_add_f32_e32 v67, 1.0, v67
	v_rcp_f32_e32 v66, v66
	v_rcp_f32_e32 v67, v67
	v_pk_mul_f32 v[60:61], v[60:61], v[64:65]
	s_nop 0
	v_pk_mul_f32 v[56:57], v[60:61], v[56:57]
	v_pk_mul_f32 v[60:61], v[62:63], v[66:67]
	v_cvt_pk_bf16_f32 v56, v56, v57
	v_mul_f32_e32 v57, 0xbfb8aa3b, v52
	v_pk_mul_f32 v[58:59], v[60:61], v[58:59]
	v_exp_f32_e32 v60, v57
	v_mul_f32_e32 v57, 0xbfb8aa3b, v53
	v_exp_f32_e32 v61, v57
	v_cvt_pk_bf16_f32 v57, v58, v59
	v_add_f32_e32 v58, 1.0, v60
	v_mul_f32_e32 v60, 0xbfb8aa3b, v54
	v_add_f32_e32 v59, 1.0, v61
	v_mul_f32_e32 v61, 0xbfb8aa3b, v55
	v_exp_f32_e32 v60, v60
	v_exp_f32_e32 v61, v61
	v_rcp_f32_e32 v58, v58
	v_rcp_f32_e32 v59, v59
	v_add_f32_e32 v60, 1.0, v60
	v_add_f32_e32 v61, 1.0, v61
	v_rcp_f32_e32 v60, v60
	v_rcp_f32_e32 v61, v61
	v_pk_mul_f32 v[52:53], v[52:53], v[58:59]
	s_nop 0
	v_pk_mul_f32 v[48:49], v[52:53], v[48:49]
	v_add_u32_e32 v52, 0x90, v150
	v_cvt_pk_bf16_f32 v58, v48, v49
	v_pk_mul_f32 v[48:49], v[54:55], v[60:61]
	s_nop 0
	v_pk_mul_f32 v[48:49], v[48:49], v[50:51]
	v_mul_f32_e32 v50, 0xbfb8aa3b, v46
	v_cvt_pk_bf16_f32 v59, v48, v49
	v_mad_i64_i32 v[48:49], s[40:41], v68, s70, v[112:113]
	v_lshl_add_u64 v[48:49], v[48:49], 0, v[114:115]
	global_store_dwordx4 v[48:49], v[56:59], off nt
	v_mul_f32_e32 v48, 0xbfb8aa3b, v44
	v_mul_f32_e32 v49, 0xbfb8aa3b, v45
	v_exp_f32_e32 v48, v48
	v_exp_f32_e32 v49, v49
	v_mul_f32_e32 v51, 0xbfb8aa3b, v47
	v_exp_f32_e32 v50, v50
	v_exp_f32_e32 v51, v51
	v_add_f32_e32 v48, 1.0, v48
	v_add_f32_e32 v49, 1.0, v49
	v_rcp_f32_e32 v48, v48
	v_rcp_f32_e32 v49, v49
	v_add_f32_e32 v50, 1.0, v50
	v_add_f32_e32 v51, 1.0, v51
	v_rcp_f32_e32 v50, v50
	v_rcp_f32_e32 v51, v51
	v_pk_mul_f32 v[44:45], v[44:45], v[48:49]
	s_nop 0
	v_pk_mul_f32 v[40:41], v[44:45], v[40:41]
	v_pk_mul_f32 v[44:45], v[46:47], v[50:51]
	v_cvt_pk_bf16_f32 v40, v40, v41
	v_mul_f32_e32 v41, 0xbfb8aa3b, v36
	v_pk_mul_f32 v[42:43], v[44:45], v[42:43]
	v_exp_f32_e32 v44, v41
	v_mul_f32_e32 v41, 0xbfb8aa3b, v37
	v_exp_f32_e32 v45, v41
	v_cvt_pk_bf16_f32 v41, v42, v43
	v_add_f32_e32 v42, 1.0, v44
	v_mul_f32_e32 v44, 0xbfb8aa3b, v38
	v_add_f32_e32 v43, 1.0, v45
	v_mul_f32_e32 v45, 0xbfb8aa3b, v39
	v_exp_f32_e32 v44, v44
	v_exp_f32_e32 v45, v45
	v_rcp_f32_e32 v42, v42
; __device__ __forceinline__ unsigned pk2(float lo, float hi) { f32x2 v = {lo, hi}; bf16x2_t b = __builtin_convertvector(v, bf16x2_t); return __builtin_bit_cast(unsigned, b); }
; __device__ __forceinline__ float silu_f(float a) { return a * __builtin_amdgcn_rcpf(1.0f + __expf(-a)); }
; #define PG8_BAR __builtin_amdgcn_s_barrier()
;     __device__ __forceinline__ void operator()(const f32x4 (&acc)[2][2][4][2], const Unit& u, int wr, int wc, int fr, int fq) const {
;     ...
;             for (int m = 0; m < 4; ++m) { const int row = row0 + ai * HALF + m * 16;
;                 const f32x4 a0 = acc[ai][0][m][0], a1 = acc[ai][0][m][1], b0 = acc[ai][1][m][0], b1 = acc[ai][1][m][1];
;                 u32x4 w; w.x = pk2(silu_f(a0[0]) * b0[0], silu_f(a0[1]) * b0[1]); w.y = pk2(silu_f(a0[2]) * b0[2], silu_f(a0[3]) * b0[3]);
;                 w.z = pk2(silu_f(a1[0]) * b1[0], silu_f(a1[1]) * b1[1]); w.w = pk2(silu_f(a1[2]) * b1[2], silu_f(a1[3]) * b1[3]);
;                 *(u32x4*)(H + (size_t)row * ldh + col0) = w; }
; template <class Epi, class Sched, bool ALIGN_EPI = false, bool SP2 = false>
; __device__ __forceinline__ void gemm_phase(PG8_LAS unsigned char* lds, const Gemm g, const Sched& S, const Epi& E) {
;     ...
;         if (!has_next) break;
; #pragma unroll
;         for (int a = 0; a < 2; ++a)
; #pragma unroll
;             for (int b = 0; b < 2; ++b)
; #pragma unroll
;                 for (int m = 0; m < 4; ++m)
; #pragma unroll
;                     for (int n = 0; n < 2; ++n) acc[a][b][m][n] = (f32x4){0.f, 0.f, 0.f, 0.f};
;         cur = nxt; cA = nA; cB = nB; ++ui;
;         if constexpr (ALIGN_EPI) { if (wr == 1) PG8_BAR; }
	v_rcp_f32_e32 v43, v43
	v_add_f32_e32 v44, 1.0, v44
	v_add_f32_e32 v45, 1.0, v45
	v_rcp_f32_e32 v44, v44
	v_rcp_f32_e32 v45, v45
	v_pk_mul_f32 v[36:37], v[36:37], v[42:43]
	s_nop 0
	v_pk_mul_f32 v[32:33], v[36:37], v[32:33]
	v_add_u32_e32 v36, 0xa0, v150
	v_cvt_pk_bf16_f32 v42, v32, v33
	v_pk_mul_f32 v[32:33], v[38:39], v[44:45]
	s_nop 0
	v_pk_mul_f32 v[32:33], v[32:33], v[34:35]
	v_mul_f32_e32 v34, 0xbfb8aa3b, v30
	v_cvt_pk_bf16_f32 v43, v32, v33
	v_mad_i64_i32 v[32:33], s[40:41], v52, s70, v[112:113]
	v_lshl_add_u64 v[32:33], v[32:33], 0, v[114:115]
	global_store_dwordx4 v[32:33], v[40:43], off nt
	v_mul_f32_e32 v32, 0xbfb8aa3b, v28
	v_mul_f32_e32 v33, 0xbfb8aa3b, v29
	v_exp_f32_e32 v32, v32
	v_exp_f32_e32 v33, v33
	v_mul_f32_e32 v35, 0xbfb8aa3b, v31
	v_exp_f32_e32 v34, v34
	v_exp_f32_e32 v35, v35
	v_add_f32_e32 v32, 1.0, v32
	v_add_f32_e32 v33, 1.0, v33
	v_rcp_f32_e32 v32, v32
	v_rcp_f32_e32 v33, v33
	v_add_f32_e32 v34, 1.0, v34
	v_add_f32_e32 v35, 1.0, v35
	v_rcp_f32_e32 v34, v34
	v_rcp_f32_e32 v35, v35
	v_pk_mul_f32 v[28:29], v[28:29], v[32:33]
	s_nop 0
	v_pk_mul_f32 v[24:25], v[28:29], v[24:25]
	v_pk_mul_f32 v[28:29], v[30:31], v[34:35]
	v_cvt_pk_bf16_f32 v24, v24, v25
	v_mul_f32_e32 v25, 0xbfb8aa3b, v20
	v_pk_mul_f32 v[26:27], v[28:29], v[26:27]
	v_exp_f32_e32 v28, v25
	v_mul_f32_e32 v25, 0xbfb8aa3b, v21
	v_exp_f32_e32 v29, v25
	v_cvt_pk_bf16_f32 v25, v26, v27
	v_add_f32_e32 v26, 1.0, v28
	v_mul_f32_e32 v28, 0xbfb8aa3b, v22
	v_add_f32_e32 v27, 1.0, v29
	v_mul_f32_e32 v29, 0xbfb8aa3b, v23
	v_exp_f32_e32 v28, v28
	v_exp_f32_e32 v29, v29
	v_rcp_f32_e32 v26, v26
	v_rcp_f32_e32 v27, v27
	v_add_f32_e32 v28, 1.0, v28
	v_add_f32_e32 v29, 1.0, v29
	v_rcp_f32_e32 v28, v28
	v_rcp_f32_e32 v29, v29
	v_pk_mul_f32 v[20:21], v[20:21], v[26:27]
	s_nop 0
	v_pk_mul_f32 v[16:17], v[20:21], v[16:17]
	v_add_u32_e32 v20, 0xb0, v150
	v_cvt_pk_bf16_f32 v26, v16, v17
	v_pk_mul_f32 v[16:17], v[22:23], v[28:29]
	s_nop 0
	v_pk_mul_f32 v[16:17], v[16:17], v[18:19]
	v_mul_f32_e32 v18, 0xbfb8aa3b, v14
	v_cvt_pk_bf16_f32 v27, v16, v17
	v_mad_i64_i32 v[16:17], s[40:41], v36, s70, v[112:113]
	v_lshl_add_u64 v[16:17], v[16:17], 0, v[114:115]
	global_store_dwordx4 v[16:17], v[24:27], off nt
	v_mul_f32_e32 v16, 0xbfb8aa3b, v12
	v_mul_f32_e32 v17, 0xbfb8aa3b, v13
	v_exp_f32_e32 v16, v16
	v_exp_f32_e32 v17, v17
	v_mul_f32_e32 v19, 0xbfb8aa3b, v15
	v_exp_f32_e32 v18, v18
	v_exp_f32_e32 v19, v19
	v_add_f32_e32 v16, 1.0, v16
	v_add_f32_e32 v17, 1.0, v17
	v_rcp_f32_e32 v16, v16
	v_rcp_f32_e32 v17, v17
	v_add_f32_e32 v18, 1.0, v18
	v_add_f32_e32 v19, 1.0, v19
	v_rcp_f32_e32 v18, v18
	v_rcp_f32_e32 v19, v19
	v_pk_mul_f32 v[12:13], v[12:13], v[16:17]
	s_nop 0
	v_pk_mul_f32 v[8:9], v[12:13], v[8:9]
	v_pk_mul_f32 v[12:13], v[14:15], v[18:19]
	v_cvt_pk_bf16_f32 v8, v8, v9
	v_mul_f32_e32 v9, 0xbfb8aa3b, v4
	v_pk_mul_f32 v[10:11], v[12:13], v[10:11]
	v_exp_f32_e32 v12, v9
	v_mul_f32_e32 v9, 0xbfb8aa3b, v5
	v_exp_f32_e32 v13, v9
	v_cvt_pk_bf16_f32 v9, v10, v11
	v_add_f32_e32 v10, 1.0, v12
	v_mul_f32_e32 v12, 0xbfb8aa3b, v6
	v_add_f32_e32 v11, 1.0, v13
	v_mul_f32_e32 v13, 0xbfb8aa3b, v7
	v_exp_f32_e32 v12, v12
	v_exp_f32_e32 v13, v13
	v_rcp_f32_e32 v10, v10
	v_rcp_f32_e32 v11, v11
	v_add_f32_e32 v12, 1.0, v12
	v_add_f32_e32 v13, 1.0, v13
	v_rcp_f32_e32 v12, v12
	v_rcp_f32_e32 v13, v13
	v_pk_mul_f32 v[4:5], v[4:5], v[10:11]
	s_nop 0
	v_pk_mul_f32 v[0:1], v[4:5], v[0:1]
	s_nop 0
	v_cvt_pk_bf16_f32 v10, v0, v1
	v_pk_mul_f32 v[0:1], v[6:7], v[12:13]
	s_nop 0
	v_pk_mul_f32 v[0:1], v[0:1], v[2:3]
	s_nop 0
	v_cvt_pk_bf16_f32 v11, v0, v1
	v_mad_i64_i32 v[0:1], s[40:41], v20, s70, v[112:113]
	v_lshl_add_u64 v[0:1], v[0:1], 0, v[114:115]
	global_store_dwordx4 v[0:1], v[8:11], off nt
	s_cbranch_vccnz .LBB0_710
	s_andn2_b64 vcc, exec, s[6:7]
	s_cbranch_vccnz .LBB0_709
	s_barrier
	s_branch .LBB0_709

; __device__ __forceinline__ unsigned pk2(float lo, float hi) { f32x2 v = {lo, hi}; bf16x2_t b = __builtin_convertvector(v, bf16x2_t); return __builtin_bit_cast(unsigned, b); }
; __device__ __forceinline__ float silu_f(float a) { return a * __builtin_amdgcn_rcpf(1.0f + __expf(-a)); }
;     __device__ __forceinline__ void operator()(const f32x4 (&acc)[2][2][4][2], const Unit& u, int wr, int wc, int fr, int fq) const {
;         const int row0 = u.pm * BM + wr * 64 + fr; const int col0 = u.pn * HALF + wc * 32 + 8 * fq;
; #pragma unroll
;         for (int ai = 0; ai < 2; ++ai)
; #pragma unroll
;             for (int m = 0; m < 4; ++m) { const int row = row0 + ai * HALF + m * 16;
;                 const f32x4 a0 = acc[ai][0][m][0], a1 = acc[ai][0][m][1], b0 = acc[ai][1][m][0], b1 = acc[ai][1][m][1];
;                 u32x4 w; w.x = pk2(silu_f(a0[0]) * b0[0], silu_f(a0[1]) * b0[1]); w.y = pk2(silu_f(a0[2]) * b0[2], silu_f(a0[3]) * b0[3]);
;                 w.z = pk2(silu_f(a1[0]) * b1[0], silu_f(a1[1]) * b1[1]); w.w = pk2(silu_f(a1[2]) * b1[2], silu_f(a1[3]) * b1[3]);
;                 *(u32x4*)(H + (size_t)row * ldh + col0) = w; }
.LBB0_1345:
	s_mov_b32 s77, 1
	v_mul_f32_e32 v151, 0xbfb8aa3b, v124
	v_exp_f32_e32 v151, v151
	v_mul_f32_e32 v153, 0xbfb8aa3b, v125
	v_exp_f32_e32 v153, v153
	v_mul_f32_e32 v157, 0xbfb8aa3b, v127
	v_add_f32_e32 v151, 1.0, v151
	v_rcp_f32_e32 v156, v151
	v_add_f32_e32 v151, 1.0, v153
	v_mul_f32_e32 v153, 0xbfb8aa3b, v126
	v_exp_f32_e32 v153, v153
	v_exp_f32_e32 v159, v157
	v_rcp_f32_e32 v157, v151
	v_lshl_or_b32 v154, s57, 7, v146
	v_add_f32_e32 v151, 1.0, v153
	v_rcp_f32_e32 v158, v151
	v_add_f32_e32 v151, 1.0, v159
	v_rcp_f32_e32 v159, v151
	v_pk_mul_f32 v[124:125], v[124:125], v[156:157]
	v_lshl_add_u32 v150, s24, 8, v144
	v_pk_mul_f32 v[120:121], v[124:125], v[120:121]
	v_pk_mul_f32 v[124:125], v[126:127], v[158:159]
	v_cvt_pk_bf16_f32 v120, v120, v121
	v_mul_f32_e32 v121, 0xbfb8aa3b, v116
	v_pk_mul_f32 v[122:123], v[124:125], v[122:123]
	v_exp_f32_e32 v124, v121
	v_mul_f32_e32 v121, 0xbfb8aa3b, v117
	v_exp_f32_e32 v125, v121
	v_cvt_pk_bf16_f32 v121, v122, v123
	v_add_f32_e32 v122, 1.0, v124
	v_mul_f32_e32 v124, 0xbfb8aa3b, v118
	v_add_f32_e32 v123, 1.0, v125
	v_mul_f32_e32 v125, 0xbfb8aa3b, v119
	v_exp_f32_e32 v124, v124
	v_exp_f32_e32 v125, v125
	v_rcp_f32_e32 v122, v122
	v_rcp_f32_e32 v123, v123
	v_add_f32_e32 v124, 1.0, v124
	v_add_f32_e32 v125, 1.0, v125
	v_rcp_f32_e32 v124, v124
	v_rcp_f32_e32 v125, v125
	v_pk_mul_f32 v[116:117], v[116:117], v[122:123]
	v_ashrrev_i32_e32 v155, 31, v154
	v_pk_mul_f32 v[112:113], v[116:117], v[112:113]
	s_andn2_b64 vcc, exec, s[0:1]
	v_cvt_pk_bf16_f32 v122, v112, v113
	v_pk_mul_f32 v[112:113], v[118:119], v[124:125]
	v_mul_f32_e32 v118, 0xbfb8aa3b, v110
	v_pk_mul_f32 v[112:113], v[112:113], v[114:115]
	v_lshlrev_b64 v[114:115], 1, v[154:155]
	v_cvt_pk_bf16_f32 v123, v112, v113
	v_mov_b64_e32 v[112:113], s[8:9]
	v_mad_i64_i32 v[116:117], s[36:37], v150, s56, v[112:113]
	v_lshl_add_u64 v[116:117], v[116:117], 0, v[114:115]
	global_store_dwordx4 v[116:117], v[120:123], off nt
	v_mul_f32_e32 v116, 0xbfb8aa3b, v108
	v_mul_f32_e32 v117, 0xbfb8aa3b, v109
	v_exp_f32_e32 v116, v116
	v_exp_f32_e32 v117, v117
	v_mul_f32_e32 v119, 0xbfb8aa3b, v111
	v_exp_f32_e32 v118, v118
	v_exp_f32_e32 v119, v119
	v_add_f32_e32 v116, 1.0, v116
	v_add_f32_e32 v117, 1.0, v117
	v_rcp_f32_e32 v116, v116
	v_rcp_f32_e32 v117, v117
	v_add_f32_e32 v118, 1.0, v118
	v_add_f32_e32 v119, 1.0, v119
	v_rcp_f32_e32 v118, v118
	v_rcp_f32_e32 v119, v119
	v_pk_mul_f32 v[108:109], v[108:109], v[116:117]
	v_or_b32_e32 v120, 16, v150
	v_pk_mul_f32 v[104:105], v[108:109], v[104:105]
	v_pk_mul_f32 v[108:109], v[110:111], v[118:119]
	v_cvt_pk_bf16_f32 v104, v104, v105
	v_mul_f32_e32 v105, 0xbfb8aa3b, v100
	v_pk_mul_f32 v[106:107], v[108:109], v[106:107]
	v_exp_f32_e32 v108, v105
	v_mul_f32_e32 v105, 0xbfb8aa3b, v101
	v_exp_f32_e32 v109, v105
	v_cvt_pk_bf16_f32 v105, v106, v107
	v_add_f32_e32 v106, 1.0, v108
	v_mul_f32_e32 v108, 0xbfb8aa3b, v102
	v_add_f32_e32 v107, 1.0, v109
	v_mul_f32_e32 v109, 0xbfb8aa3b, v103
	v_exp_f32_e32 v108, v108
	v_exp_f32_e32 v109, v109
	v_rcp_f32_e32 v106, v106
	v_rcp_f32_e32 v107, v107
	v_add_f32_e32 v108, 1.0, v108
	v_add_f32_e32 v109, 1.0, v109
	v_rcp_f32_e32 v108, v108
	v_rcp_f32_e32 v109, v109
	v_pk_mul_f32 v[100:101], v[100:101], v[106:107]
	s_mov_b64 s[0:1], -1
	v_pk_mul_f32 v[96:97], v[100:101], v[96:97]
	v_or_b32_e32 v100, 32, v150
	v_cvt_pk_bf16_f32 v106, v96, v97
	v_pk_mul_f32 v[96:97], v[102:103], v[108:109]
	s_nop 0
	v_pk_mul_f32 v[96:97], v[96:97], v[98:99]
	v_mul_f32_e32 v98, 0xbfb8aa3b, v94
	v_cvt_pk_bf16_f32 v107, v96, v97
	v_mad_i64_i32 v[96:97], s[36:37], v120, s56, v[112:113]
	v_lshl_add_u64 v[96:97], v[96:97], 0, v[114:115]
	global_store_dwordx4 v[96:97], v[104:107], off nt
	v_mul_f32_e32 v96, 0xbfb8aa3b, v92
	v_mul_f32_e32 v97, 0xbfb8aa3b, v93
	v_exp_f32_e32 v96, v96
	v_exp_f32_e32 v97, v97
	v_mul_f32_e32 v99, 0xbfb8aa3b, v95
	v_exp_f32_e32 v98, v98
	v_exp_f32_e32 v99, v99
	v_add_f32_e32 v96, 1.0, v96
	v_add_f32_e32 v97, 1.0, v97
	v_rcp_f32_e32 v96, v96
	v_rcp_f32_e32 v97, v97
	v_add_f32_e32 v98, 1.0, v98
	v_add_f32_e32 v99, 1.0, v99
	v_rcp_f32_e32 v98, v98
	v_rcp_f32_e32 v99, v99
	v_pk_mul_f32 v[92:93], v[92:93], v[96:97]
	s_nop 0
	v_pk_mul_f32 v[88:89], v[92:93], v[88:89]
	v_pk_mul_f32 v[92:93], v[94:95], v[98:99]
	v_cvt_pk_bf16_f32 v88, v88, v89
	v_mul_f32_e32 v89, 0xbfb8aa3b, v84
	v_pk_mul_f32 v[90:91], v[92:93], v[90:91]
	v_exp_f32_e32 v92, v89
	v_mul_f32_e32 v89, 0xbfb8aa3b, v85
	v_exp_f32_e32 v93, v89
	v_cvt_pk_bf16_f32 v89, v90, v91
	v_add_f32_e32 v90, 1.0, v92
	v_mul_f32_e32 v92, 0xbfb8aa3b, v86
	v_add_f32_e32 v91, 1.0, v93
	v_mul_f32_e32 v93, 0xbfb8aa3b, v87
	v_exp_f32_e32 v92, v92
	v_exp_f32_e32 v93, v93
	v_rcp_f32_e32 v90, v90
	v_rcp_f32_e32 v91, v91
	v_add_f32_e32 v92, 1.0, v92
	v_add_f32_e32 v93, 1.0, v93
	v_rcp_f32_e32 v92, v92
	v_rcp_f32_e32 v93, v93
	v_pk_mul_f32 v[84:85], v[84:85], v[90:91]
	s_nop 0
	v_pk_mul_f32 v[80:81], v[84:85], v[80:81]
	v_or_b32_e32 v84, 48, v150
	v_cvt_pk_bf16_f32 v90, v80, v81
	v_pk_mul_f32 v[80:81], v[86:87], v[92:93]
	s_nop 0
	v_pk_mul_f32 v[80:81], v[80:81], v[82:83]
	v_mul_f32_e32 v82, 0xbfb8aa3b, v78
	v_cvt_pk_bf16_f32 v91, v80, v81
	v_mad_i64_i32 v[80:81], s[36:37], v100, s56, v[112:113]
	v_lshl_add_u64 v[80:81], v[80:81], 0, v[114:115]
	global_store_dwordx4 v[80:81], v[88:91], off nt
	v_mul_f32_e32 v80, 0xbfb8aa3b, v76
	v_mul_f32_e32 v81, 0xbfb8aa3b, v77
	v_exp_f32_e32 v80, v80
	v_exp_f32_e32 v81, v81
	v_mul_f32_e32 v83, 0xbfb8aa3b, v79
	v_exp_f32_e32 v82, v82
	v_exp_f32_e32 v83, v83
	v_add_f32_e32 v80, 1.0, v80
	v_add_f32_e32 v81, 1.0, v81
	v_rcp_f32_e32 v80, v80
	v_rcp_f32_e32 v81, v81
	v_add_f32_e32 v82, 1.0, v82
	v_add_f32_e32 v83, 1.0, v83
; __device__ __forceinline__ unsigned pk2(float lo, float hi) { f32x2 v = {lo, hi}; bf16x2_t b = __builtin_convertvector(v, bf16x2_t); return __builtin_bit_cast(unsigned, b); }
; __device__ __forceinline__ float silu_f(float a) { return a * __builtin_amdgcn_rcpf(1.0f + __expf(-a)); }
;     __device__ __forceinline__ void operator()(const f32x4 (&acc)[2][2][4][2], const Unit& u, int wr, int wc, int fr, int fq) const {
;     ...
;             for (int m = 0; m < 4; ++m) { const int row = row0 + ai * HALF + m * 16;
;                 const f32x4 a0 = acc[ai][0][m][0], a1 = acc[ai][0][m][1], b0 = acc[ai][1][m][0], b1 = acc[ai][1][m][1];
;                 u32x4 w; w.x = pk2(silu_f(a0[0]) * b0[0], silu_f(a0[1]) * b0[1]); w.y = pk2(silu_f(a0[2]) * b0[2], silu_f(a0[3]) * b0[3]);
;                 w.z = pk2(silu_f(a1[0]) * b1[0], silu_f(a1[1]) * b1[1]); w.w = pk2(silu_f(a1[2]) * b1[2], silu_f(a1[3]) * b1[3]);
;                 *(u32x4*)(H + (size_t)row * ldh + col0) = w; }
	v_rcp_f32_e32 v82, v82
	v_rcp_f32_e32 v83, v83
	v_pk_mul_f32 v[76:77], v[76:77], v[80:81]
	s_nop 0
	v_pk_mul_f32 v[72:73], v[76:77], v[72:73]
	v_pk_mul_f32 v[76:77], v[78:79], v[82:83]
	v_cvt_pk_bf16_f32 v72, v72, v73
	v_mul_f32_e32 v73, 0xbfb8aa3b, v68
	v_pk_mul_f32 v[74:75], v[76:77], v[74:75]
	v_exp_f32_e32 v76, v73
	v_mul_f32_e32 v73, 0xbfb8aa3b, v69
	v_exp_f32_e32 v77, v73
	v_cvt_pk_bf16_f32 v73, v74, v75
	v_add_f32_e32 v74, 1.0, v76
	v_mul_f32_e32 v76, 0xbfb8aa3b, v70
	v_add_f32_e32 v75, 1.0, v77
	v_mul_f32_e32 v77, 0xbfb8aa3b, v71
	v_exp_f32_e32 v76, v76
	v_exp_f32_e32 v77, v77
	v_rcp_f32_e32 v74, v74
	v_rcp_f32_e32 v75, v75
	v_add_f32_e32 v76, 1.0, v76
	v_add_f32_e32 v77, 1.0, v77
	v_rcp_f32_e32 v76, v76
	v_rcp_f32_e32 v77, v77
	v_pk_mul_f32 v[68:69], v[68:69], v[74:75]
	s_nop 0
	v_pk_mul_f32 v[64:65], v[68:69], v[64:65]
	v_add_u32_e32 v68, 0x80, v150
	v_cvt_pk_bf16_f32 v74, v64, v65
	v_pk_mul_f32 v[64:65], v[70:71], v[76:77]
	s_nop 0
	v_pk_mul_f32 v[64:65], v[64:65], v[66:67]
	v_mul_f32_e32 v66, 0xbfb8aa3b, v62
	v_cvt_pk_bf16_f32 v75, v64, v65
	v_mad_i64_i32 v[64:65], s[36:37], v84, s56, v[112:113]
	v_lshl_add_u64 v[64:65], v[64:65], 0, v[114:115]
	global_store_dwordx4 v[64:65], v[72:75], off nt
	v_mul_f32_e32 v64, 0xbfb8aa3b, v60
	v_mul_f32_e32 v65, 0xbfb8aa3b, v61
	v_exp_f32_e32 v64, v64
	v_exp_f32_e32 v65, v65
	v_mul_f32_e32 v67, 0xbfb8aa3b, v63
	v_exp_f32_e32 v66, v66
	v_exp_f32_e32 v67, v67
	v_add_f32_e32 v64, 1.0, v64
	v_add_f32_e32 v65, 1.0, v65
	v_rcp_f32_e32 v64, v64
	v_rcp_f32_e32 v65, v65
	v_add_f32_e32 v66, 1.0, v66
	v_add_f32_e32 v67, 1.0, v67
	v_rcp_f32_e32 v66, v66
	v_rcp_f32_e32 v67, v67
	v_pk_mul_f32 v[60:61], v[60:61], v[64:65]
	s_nop 0
	v_pk_mul_f32 v[56:57], v[60:61], v[56:57]
	v_pk_mul_f32 v[60:61], v[62:63], v[66:67]
	v_cvt_pk_bf16_f32 v56, v56, v57
	v_mul_f32_e32 v57, 0xbfb8aa3b, v52
	v_pk_mul_f32 v[58:59], v[60:61], v[58:59]
	v_exp_f32_e32 v60, v57
	v_mul_f32_e32 v57, 0xbfb8aa3b, v53
	v_exp_f32_e32 v61, v57
	v_cvt_pk_bf16_f32 v57, v58, v59
	v_add_f32_e32 v58, 1.0, v60
	v_mul_f32_e32 v60, 0xbfb8aa3b, v54
	v_add_f32_e32 v59, 1.0, v61
	v_mul_f32_e32 v61, 0xbfb8aa3b, v55
	v_exp_f32_e32 v60, v60
	v_exp_f32_e32 v61, v61
	v_rcp_f32_e32 v58, v58
	v_rcp_f32_e32 v59, v59
	v_add_f32_e32 v60, 1.0, v60
	v_add_f32_e32 v61, 1.0, v61
	v_rcp_f32_e32 v60, v60
	v_rcp_f32_e32 v61, v61
	v_pk_mul_f32 v[52:53], v[52:53], v[58:59]
	s_nop 0
	v_pk_mul_f32 v[48:49], v[52:53], v[48:49]
	v_add_u32_e32 v52, 0x90, v150
	v_cvt_pk_bf16_f32 v58, v48, v49
	v_pk_mul_f32 v[48:49], v[54:55], v[60:61]
	s_nop 0
	v_pk_mul_f32 v[48:49], v[48:49], v[50:51]
	v_mul_f32_e32 v50, 0xbfb8aa3b, v46
	v_cvt_pk_bf16_f32 v59, v48, v49
	v_mad_i64_i32 v[48:49], s[36:37], v68, s56, v[112:113]
	v_lshl_add_u64 v[48:49], v[48:49], 0, v[114:115]
	global_store_dwordx4 v[48:49], v[56:59], off nt
	v_mul_f32_e32 v48, 0xbfb8aa3b, v44
	v_mul_f32_e32 v49, 0xbfb8aa3b, v45
	v_exp_f32_e32 v48, v48
	v_exp_f32_e32 v49, v49
	v_mul_f32_e32 v51, 0xbfb8aa3b, v47
	v_exp_f32_e32 v50, v50
	v_exp_f32_e32 v51, v51
	v_add_f32_e32 v48, 1.0, v48
	v_add_f32_e32 v49, 1.0, v49
	v_rcp_f32_e32 v48, v48
	v_rcp_f32_e32 v49, v49
	v_add_f32_e32 v50, 1.0, v50
	v_add_f32_e32 v51, 1.0, v51
	v_rcp_f32_e32 v50, v50
	v_rcp_f32_e32 v51, v51
	v_pk_mul_f32 v[44:45], v[44:45], v[48:49]
	s_nop 0
	v_pk_mul_f32 v[40:41], v[44:45], v[40:41]
	v_pk_mul_f32 v[44:45], v[46:47], v[50:51]
	v_cvt_pk_bf16_f32 v40, v40, v41
	v_mul_f32_e32 v41, 0xbfb8aa3b, v36
	v_pk_mul_f32 v[42:43], v[44:45], v[42:43]
	v_exp_f32_e32 v44, v41
	v_mul_f32_e32 v41, 0xbfb8aa3b, v37
	v_exp_f32_e32 v45, v41
	v_cvt_pk_bf16_f32 v41, v42, v43
	v_add_f32_e32 v42, 1.0, v44
	v_mul_f32_e32 v44, 0xbfb8aa3b, v38
	v_add_f32_e32 v43, 1.0, v45
	v_mul_f32_e32 v45, 0xbfb8aa3b, v39
	v_exp_f32_e32 v44, v44
	v_exp_f32_e32 v45, v45
	v_rcp_f32_e32 v42, v42
; __device__ __forceinline__ unsigned pk2(float lo, float hi) { f32x2 v = {lo, hi}; bf16x2_t b = __builtin_convertvector(v, bf16x2_t); return __builtin_bit_cast(unsigned, b); }
; __device__ __forceinline__ float silu_f(float a) { return a * __builtin_amdgcn_rcpf(1.0f + __expf(-a)); }
; #define PG8_BAR __builtin_amdgcn_s_barrier()
;     __device__ __forceinline__ void operator()(const f32x4 (&acc)[2][2][4][2], const Unit& u, int wr, int wc, int fr, int fq) const {
;     ...
;             for (int m = 0; m < 4; ++m) { const int row = row0 + ai * HALF + m * 16;
;                 const f32x4 a0 = acc[ai][0][m][0], a1 = acc[ai][0][m][1], b0 = acc[ai][1][m][0], b1 = acc[ai][1][m][1];
;                 u32x4 w; w.x = pk2(silu_f(a0[0]) * b0[0], silu_f(a0[1]) * b0[1]); w.y = pk2(silu_f(a0[2]) * b0[2], silu_f(a0[3]) * b0[3]);
;                 w.z = pk2(silu_f(a1[0]) * b1[0], silu_f(a1[1]) * b1[1]); w.w = pk2(silu_f(a1[2]) * b1[2], silu_f(a1[3]) * b1[3]);
;                 *(u32x4*)(H + (size_t)row * ldh + col0) = w; }
; template <class Epi, class Sched, bool ALIGN_EPI = false, bool SP2 = false>
; __device__ __forceinline__ void gemm_phase(PG8_LAS unsigned char* lds, const Gemm g, const Sched& S, const Epi& E) {
;     ...
;         if (!has_next) break;
; #pragma unroll
;         for (int a = 0; a < 2; ++a)
; #pragma unroll
;             for (int b = 0; b < 2; ++b)
; #pragma unroll
;                 for (int m = 0; m < 4; ++m)
; #pragma unroll
;                     for (int n = 0; n < 2; ++n) acc[a][b][m][n] = (f32x4){0.f, 0.f, 0.f, 0.f};
;         cur = nxt; cA = nA; cB = nB; ++ui;
;         if constexpr (ALIGN_EPI) { if (wr == 1) PG8_BAR; }
	v_rcp_f32_e32 v43, v43
	v_add_f32_e32 v44, 1.0, v44
	v_add_f32_e32 v45, 1.0, v45
	v_rcp_f32_e32 v44, v44
	v_rcp_f32_e32 v45, v45
	v_pk_mul_f32 v[36:37], v[36:37], v[42:43]
	s_nop 0
	v_pk_mul_f32 v[32:33], v[36:37], v[32:33]
	v_add_u32_e32 v36, 0xa0, v150
	v_cvt_pk_bf16_f32 v42, v32, v33
	v_pk_mul_f32 v[32:33], v[38:39], v[44:45]
	s_nop 0
	v_pk_mul_f32 v[32:33], v[32:33], v[34:35]
	v_mul_f32_e32 v34, 0xbfb8aa3b, v30
	v_cvt_pk_bf16_f32 v43, v32, v33
	v_mad_i64_i32 v[32:33], s[36:37], v52, s56, v[112:113]
	v_lshl_add_u64 v[32:33], v[32:33], 0, v[114:115]
	global_store_dwordx4 v[32:33], v[40:43], off nt
	v_mul_f32_e32 v32, 0xbfb8aa3b, v28
	v_mul_f32_e32 v33, 0xbfb8aa3b, v29
	v_exp_f32_e32 v32, v32
	v_exp_f32_e32 v33, v33
	v_mul_f32_e32 v35, 0xbfb8aa3b, v31
	v_exp_f32_e32 v34, v34
	v_exp_f32_e32 v35, v35
	v_add_f32_e32 v32, 1.0, v32
	v_add_f32_e32 v33, 1.0, v33
	v_rcp_f32_e32 v32, v32
	v_rcp_f32_e32 v33, v33
	v_add_f32_e32 v34, 1.0, v34
	v_add_f32_e32 v35, 1.0, v35
	v_rcp_f32_e32 v34, v34
	v_rcp_f32_e32 v35, v35
	v_pk_mul_f32 v[28:29], v[28:29], v[32:33]
	s_nop 0
	v_pk_mul_f32 v[24:25], v[28:29], v[24:25]
	v_pk_mul_f32 v[28:29], v[30:31], v[34:35]
	v_cvt_pk_bf16_f32 v24, v24, v25
	v_mul_f32_e32 v25, 0xbfb8aa3b, v20
	v_pk_mul_f32 v[26:27], v[28:29], v[26:27]
	v_exp_f32_e32 v28, v25
	v_mul_f32_e32 v25, 0xbfb8aa3b, v21
	v_exp_f32_e32 v29, v25
	v_cvt_pk_bf16_f32 v25, v26, v27
	v_add_f32_e32 v26, 1.0, v28
	v_mul_f32_e32 v28, 0xbfb8aa3b, v22
	v_add_f32_e32 v27, 1.0, v29
	v_mul_f32_e32 v29, 0xbfb8aa3b, v23
	v_exp_f32_e32 v28, v28
	v_exp_f32_e32 v29, v29
	v_rcp_f32_e32 v26, v26
	v_rcp_f32_e32 v27, v27
	v_add_f32_e32 v28, 1.0, v28
	v_add_f32_e32 v29, 1.0, v29
	v_rcp_f32_e32 v28, v28
	v_rcp_f32_e32 v29, v29
	v_pk_mul_f32 v[20:21], v[20:21], v[26:27]
	s_nop 0
	v_pk_mul_f32 v[16:17], v[20:21], v[16:17]
	v_add_u32_e32 v20, 0xb0, v150
	v_cvt_pk_bf16_f32 v26, v16, v17
	v_pk_mul_f32 v[16:17], v[22:23], v[28:29]
	s_nop 0
	v_pk_mul_f32 v[16:17], v[16:17], v[18:19]
	v_mul_f32_e32 v18, 0xbfb8aa3b, v14
	v_cvt_pk_bf16_f32 v27, v16, v17
	v_mad_i64_i32 v[16:17], s[36:37], v36, s56, v[112:113]
	v_lshl_add_u64 v[16:17], v[16:17], 0, v[114:115]
	global_store_dwordx4 v[16:17], v[24:27], off nt
	v_mul_f32_e32 v16, 0xbfb8aa3b, v12
	v_mul_f32_e32 v17, 0xbfb8aa3b, v13
	v_exp_f32_e32 v16, v16
	v_exp_f32_e32 v17, v17
	v_mul_f32_e32 v19, 0xbfb8aa3b, v15
	v_exp_f32_e32 v18, v18
	v_exp_f32_e32 v19, v19
	v_add_f32_e32 v16, 1.0, v16
	v_add_f32_e32 v17, 1.0, v17
	v_rcp_f32_e32 v16, v16
	v_rcp_f32_e32 v17, v17
	v_add_f32_e32 v18, 1.0, v18
	v_add_f32_e32 v19, 1.0, v19
	v_rcp_f32_e32 v18, v18
	v_rcp_f32_e32 v19, v19
	v_pk_mul_f32 v[12:13], v[12:13], v[16:17]
	s_nop 0
	v_pk_mul_f32 v[8:9], v[12:13], v[8:9]
	v_pk_mul_f32 v[12:13], v[14:15], v[18:19]
	v_cvt_pk_bf16_f32 v8, v8, v9
	v_mul_f32_e32 v9, 0xbfb8aa3b, v4
	v_pk_mul_f32 v[10:11], v[12:13], v[10:11]
	v_exp_f32_e32 v12, v9
	v_mul_f32_e32 v9, 0xbfb8aa3b, v5
	v_exp_f32_e32 v13, v9
	v_cvt_pk_bf16_f32 v9, v10, v11
	v_add_f32_e32 v10, 1.0, v12
	v_mul_f32_e32 v12, 0xbfb8aa3b, v6
	v_add_f32_e32 v11, 1.0, v13
	v_mul_f32_e32 v13, 0xbfb8aa3b, v7
	v_exp_f32_e32 v12, v12
	v_exp_f32_e32 v13, v13
	v_rcp_f32_e32 v10, v10
	v_rcp_f32_e32 v11, v11
	v_add_f32_e32 v12, 1.0, v12
	v_add_f32_e32 v13, 1.0, v13
	v_rcp_f32_e32 v12, v12
	v_rcp_f32_e32 v13, v13
	v_pk_mul_f32 v[4:5], v[4:5], v[10:11]
	s_nop 0
	v_pk_mul_f32 v[0:1], v[4:5], v[0:1]
	s_nop 0
	v_cvt_pk_bf16_f32 v10, v0, v1
	v_pk_mul_f32 v[0:1], v[6:7], v[12:13]
	s_nop 0
	v_pk_mul_f32 v[0:1], v[0:1], v[2:3]
	s_nop 0
	v_cvt_pk_bf16_f32 v11, v0, v1
	v_mad_i64_i32 v[0:1], s[36:37], v20, s56, v[112:113]
	v_lshl_add_u64 v[0:1], v[0:1], 0, v[114:115]
	global_store_dwordx4 v[0:1], v[8:11], off nt
	s_cbranch_vccnz .LBB0_1338
	s_andn2_b64 vcc, exec, s[6:7]
	s_cbranch_vccnz .LBB0_1337
	s_barrier
	s_branch .LBB0_1337
